# WKV scan: prep waves at s_setprio 2 only for their chunk-top load issue and y store section (partial priority raise)
# baseline (speedup 1.0000x reference)
.LBB0_550:
	s_setprio 0
	s_andn2_b64 vcc, exec, s[4:5]
	s_cbranch_vccnz .LBB0_555
	v_lshlrev_b32_e32 v2, 16, v96
	v_and_b32_e32 v3, 0xffff0000, v96
	v_lshlrev_b32_e32 v32, 16, v97
	v_and_b32_e32 v33, 0xffff0000, v97
	v_pk_mul_f32 v[40:41], v[4:5], v[2:3]
	v_pk_mul_f32 v[42:43], v[6:7], v[32:33]
	v_pk_mul_f32 v[36:37], v[40:41], v[40:41]
	v_pk_mul_f32 v[34:35], v[42:43], v[42:43]
	v_lshlrev_b32_e32 v44, 16, v102
	v_pk_mov_b32 v[38:39], v[36:37], v[34:35] op_sel:[1,0]
	v_mov_b32_e32 v37, v35
	v_pk_add_f32 v[34:35], v[38:39], v[36:37]
	v_and_b32_e32 v45, 0xffff0000, v102
	v_lshlrev_b32_e32 v46, 16, v103
	v_and_b32_e32 v47, 0xffff0000, v103
	v_add_f32_e32 v0, v34, v35
	v_pk_add_f32 v[34:35], v[46:47], -1.0 op_sel_hi:[1,0]
	v_pk_add_f32 v[36:37], v[44:45], -1.0 op_sel_hi:[1,0]
	v_add_f32_dpp v0, v0, v0 quad_perm:[1,0,3,2] row_mask:0xf bank_mask:0xf bound_ctrl:1
	v_pk_fma_f32 v[36:37], v[8:9], v[36:37], 1.0 op_sel_hi:[1,1,0]
	v_pk_fma_f32 v[34:35], v[10:11], v[34:35], 1.0 op_sel_hi:[1,1,0]
	v_add_f32_dpp v0, v0, v0 quad_perm:[2,3,0,1] row_mask:0xf bank_mask:0xf bound_ctrl:1
	v_lshlrev_b32_e32 v24, 16, v94
	v_and_b32_e32 v25, 0xffff0000, v94
	v_add_f32_dpp v0, v0, v0 row_half_mirror row_mask:0xf bank_mask:0xf bound_ctrl:1
	v_pk_mul_f32 v[34:35], v[34:35], v[32:33]
	v_pk_mul_f32 v[32:33], v[36:37], v[2:3]
	v_lshlrev_b32_e32 v26, 16, v95
	v_and_b32_e32 v27, 0xffff0000, v95
	v_add_f32_dpp v0, v0, v0 row_mirror row_mask:0xf bank_mask:0xf bound_ctrl:1
	v_pk_mul_f32 v[2:3], v[32:33], v[24:25]
	v_lshlrev_b32_e32 v49, 16, v100
	v_max_f32_e32 v0, 0x179abe15, v0
	v_pk_mul_f32 v[36:37], v[34:35], v[26:27]
	v_pk_mul_f32 v[2:3], v[12:13], v[2:3]
	v_and_b32_e32 v50, 0xffff0000, v100
	v_rsq_f32_e32 v48, v0
	v_pk_mul_f32 v[36:37], v[14:15], v[36:37]
	v_add_f32_e32 v0, v2, v3
	v_mul_f32_e32 v3, 0xbfb8aa3b, v49
	v_lshlrev_b32_e32 v51, 16, v101
	v_add_f32_e32 v2, v36, v37
	v_exp_f32_e32 v36, v3
	v_mul_f32_e32 v3, 0xbfb8aa3b, v50
	v_and_b32_e32 v52, 0xffff0000, v101
	v_exp_f32_e32 v37, v3
	v_mul_f32_e32 v3, 0xbfb8aa3b, v51
	v_add_f32_e32 v0, v0, v2
	v_exp_f32_e32 v38, v3
	v_mul_f32_e32 v3, 0xbfb8aa3b, v52
	v_add_f32_dpp v0, v0, v0 quad_perm:[1,0,3,2] row_mask:0xf bank_mask:0xf bound_ctrl:1
	v_exp_f32_e32 v39, v3
	s_xor_b32 s4, s93, 1
	v_add_f32_dpp v0, v0, v0 quad_perm:[2,3,0,1] row_mask:0xf bank_mask:0xf bound_ctrl:1
	s_mulk_i32 s4, 0x6000
	v_pk_mul_f32 v[42:43], v[42:43], v[48:49] op_sel_hi:[1,0]
	v_add_f32_dpp v0, v0, v0 row_half_mirror row_mask:0xf bank_mask:0xf bound_ctrl:1
	v_pk_mul_f32 v[40:41], v[40:41], v[48:49] op_sel_hi:[1,0]
	v_add_u32_e32 v3, s4, v69
	v_lshlrev_b32_e32 v28, 16, v98
	v_and_b32_e32 v29, 0xffff0000, v98
	v_lshlrev_b32_e32 v30, 16, v99
	v_and_b32_e32 v31, 0xffff0000, v99
	v_mov_b32_dpp v2, v0 row_mirror row_mask:0xf bank_mask:0xf bound_ctrl:1
	ds_write_b128 v3, v[24:27]
	ds_write_b128 v3, v[36:39] offset:4096
	ds_write_b128 v3, v[32:35] offset:8192
	ds_write_b128 v3, v[28:31] offset:12288
	v_add_u32_e32 v197, 0x1d000, v3
	ds_write2_b32 v197, v29, v28 offset1:1
	ds_write2_b32 v197, v31, v30 offset0:2 offset1:3
	ds_write_b128 v3, v[40:43] offset:16384
	v_pk_mul_f32 v[26:27], v[42:43], v[46:47]
	v_pk_mul_f32 v[24:25], v[40:41], v[44:45]
	ds_write_b128 v3, v[24:27] offset:20480
	s_and_saveexec_b64 s[4:5], s[2:3]
	s_cbranch_execz .LBB0_553
	v_add_u32_e32 v24, s91, v142
	v_ashrrev_i32_e32 v25, 31, v24
	v_lshlrev_b64 v[24:25], 6, v[24:25]
	v_lshl_add_u64 v[24:25], s[52:53], 0, v[24:25]
	v_add_f32_e32 v0, v0, v2
	global_store_dword v[24:25], v0, off
